# counted lgkmcnt waits before each MFMA in the NSA and differential-attention tile bodies (wait only for the fragment consumed)
# speedup vs baseline: 1.0548x; 1.0204x over previous
; DI unsigned pk2(float a, float b) { f32x2 v = {a, b}; bf16x2_t r = __builtin_convertvector(v, bf16x2_t); return __builtin_bit_cast(unsigned, r); }
; DI f32x4 mfma16(bf16x8 a, bf16x8 b, f32x4 c) { return __builtin_amdgcn_mfma_f32_16x16x32_bf16(a, b, c, 0, 0, 0); }
; #define SB0 __builtin_amdgcn_sched_barrier(0)
; DI void diff_PV(f32x4 (&o0)[8], f32x4 (&o1)[8], const char* Vb, const bf16x8 (&p0)[2], const bf16x8 (&p1)[2], bf16x8 (&v0)[4], bf16x8 (&v1)[4], int lr, int quad) {
;   bf16x8 v2[4], v3[4];
;   SB0;
;   ldv4(v2, Vb, 2, lr, quad);
;   __builtin_amdgcn_s_setprio(1);
; #pragma unroll
;   for (int i = 0; i < 4; ++i) { o0[i] = mfma16(v0[i], p0[0], o0[i]); o1[i] = mfma16(v0[i], p1[0], o1[i]); }
;   __builtin_amdgcn_s_setprio(0);
;   SB0;
;   ldv4(v3, Vb, 3, lr, quad);
;   __builtin_amdgcn_s_setprio(1);
; #pragma unroll
;   for (int i = 0; i < 4; ++i) { o0[4 + i] = mfma16(v1[i], p0[0], o0[4 + i]); o1[4 + i] = mfma16(v1[i], p1[0], o1[4 + i]); }
;   __builtin_amdgcn_s_setprio(0);
;   SB0;
;   __builtin_amdgcn_s_setprio(1);
; #pragma unroll
;   for (int i = 0; i < 4; ++i) { o0[i] = mfma16(v2[i], p0[1], o0[i]); o1[i] = mfma16(v2[i], p1[1], o1[i]); }
;   __builtin_amdgcn_s_setprio(0);
;   __builtin_amdgcn_s_setprio(1);
; #pragma unroll
;   for (int i = 0; i < 4; ++i) { o0[4 + i] = mfma16(v3[i], p0[1], o0[4 + i]); o1[4 + i] = mfma16(v3[i], p1[1], o1[4 + i]); }
;   __builtin_amdgcn_s_setprio(0);
; }
; DI void pack_p(const f32x4 (&s)[4], bf16x8 (&pf)[2]) {
; #pragma unroll
;   for (int s2 = 0; s2 < 2; ++s2)
;     pf[s2] = mk8(pk2(s[2 * s2][0], s[2 * s2][1]), pk2(s[2 * s2][2], s[2 * s2][3]),
;                  pk2(s[2 * s2 + 1][0], s[2 * s2 + 1][1]), pk2(s[2 * s2 + 1][2], s[2 * s2 + 1][3]));
; }
.LBB0_569:
	s_or_b64 exec, exec, s[50:51]
	v_add_f32_e32 v219, v219, v231
	v_cvt_pk_bf16_f32 v0, v0, v1
	v_cvt_pk_bf16_f32 v1, v2, v3
	v_cvt_pk_bf16_f32 v2, v4, v5
	v_cvt_pk_bf16_f32 v3, v6, v7
	v_cvt_pk_bf16_f32 v4, v8, v9
	v_cvt_pk_bf16_f32 v5, v10, v11
	v_cvt_pk_bf16_f32 v6, v12, v13
	v_cvt_pk_bf16_f32 v7, v14, v15
	v_cvt_pk_bf16_f32 v8, v16, v17
	v_cvt_pk_bf16_f32 v9, v18, v19
	v_cvt_pk_bf16_f32 v10, v20, v21
	v_cvt_pk_bf16_f32 v11, v22, v23
	v_cvt_pk_bf16_f32 v12, v24, v25
	v_cvt_pk_bf16_f32 v13, v26, v27
	v_cvt_pk_bf16_f32 v14, v28, v29
	v_cvt_pk_bf16_f32 v15, v30, v31
	v_add3_u32 v144, s67, v218, v216
	ds_read_b128 v[16:19], v144 offset:16384
	ds_read_b128 v[20:23], v144 offset:18432
	ds_read_b128 v[24:27], v144 offset:20480
	ds_read_b128 v[28:31], v144 offset:22528
	s_setprio 1
	s_waitcnt lgkmcnt(4)
	v_mfma_f32_16x16x32_bf16 v[92:95], v[140:143], v[0:3], v[92:95]
	v_mfma_f32_16x16x32_bf16 v[60:63], v[140:143], v[8:11], v[60:63]
	v_mfma_f32_16x16x32_bf16 v[88:91], v[136:139], v[0:3], v[88:91]
	v_mfma_f32_16x16x32_bf16 v[56:59], v[136:139], v[8:11], v[56:59]
	v_mfma_f32_16x16x32_bf16 v[84:87], v[128:131], v[0:3], v[84:87]
	v_mfma_f32_16x16x32_bf16 v[52:55], v[128:131], v[8:11], v[52:55]
	v_mfma_f32_16x16x32_bf16 v[80:83], v[120:123], v[0:3], v[80:83]
	v_mfma_f32_16x16x32_bf16 v[48:51], v[120:123], v[8:11], v[48:51]
	s_setprio 0
	ds_read_b128 v[120:123], v144 offset:24576
	ds_read_b128 v[128:131], v144 offset:26624
	ds_read_b128 v[136:139], v144 offset:28672
	ds_read_b128 v[140:143], v144 offset:30720
	s_setprio 1
	v_mfma_f32_16x16x32_bf16 v[76:79], v[132:135], v[0:3], v[76:79]
	v_mfma_f32_16x16x32_bf16 v[44:47], v[132:135], v[8:11], v[44:47]
	v_mfma_f32_16x16x32_bf16 v[72:75], v[124:127], v[0:3], v[72:75]
	v_mfma_f32_16x16x32_bf16 v[40:43], v[124:127], v[8:11], v[40:43]
	v_mfma_f32_16x16x32_bf16 v[68:71], v[116:119], v[0:3], v[68:71]
	v_mfma_f32_16x16x32_bf16 v[36:39], v[116:119], v[8:11], v[36:39]
	v_mfma_f32_16x16x32_bf16 v[0:3], v[112:115], v[0:3], v[64:67]
	v_mfma_f32_16x16x32_bf16 v[8:11], v[112:115], v[8:11], v[32:35]
	s_setprio 0
	s_setprio 1
	s_waitcnt lgkmcnt(7)
	v_mfma_f32_16x16x32_bf16 v[92:95], v[16:19], v[4:7], v[92:95]
	v_mfma_f32_16x16x32_bf16 v[60:63], v[16:19], v[12:15], v[60:63]
	s_waitcnt lgkmcnt(6)
	v_mfma_f32_16x16x32_bf16 v[88:91], v[20:23], v[4:7], v[88:91]
	v_mfma_f32_16x16x32_bf16 v[56:59], v[20:23], v[12:15], v[56:59]
	s_waitcnt lgkmcnt(5)
	v_mfma_f32_16x16x32_bf16 v[84:87], v[24:27], v[4:7], v[84:87]
	v_mfma_f32_16x16x32_bf16 v[52:55], v[24:27], v[12:15], v[52:55]
	s_waitcnt lgkmcnt(4)
	v_mfma_f32_16x16x32_bf16 v[80:83], v[28:31], v[4:7], v[80:83]
	v_mfma_f32_16x16x32_bf16 v[48:51], v[28:31], v[12:15], v[48:51]
	s_setprio 0
	s_setprio 1
	s_waitcnt lgkmcnt(3)
	v_mfma_f32_16x16x32_bf16 v[76:79], v[120:123], v[4:7], v[76:79]
	v_mfma_f32_16x16x32_bf16 v[44:47], v[120:123], v[12:15], v[44:47]
	s_waitcnt lgkmcnt(2)
	v_mfma_f32_16x16x32_bf16 v[72:75], v[128:131], v[4:7], v[72:75]
	v_mfma_f32_16x16x32_bf16 v[40:43], v[128:131], v[12:15], v[40:43]
	s_waitcnt lgkmcnt(1)
	v_mfma_f32_16x16x32_bf16 v[68:71], v[136:139], v[4:7], v[68:71]
	v_mfma_f32_16x16x32_bf16 v[36:39], v[136:139], v[12:15], v[36:39]
	s_waitcnt lgkmcnt(0)
	v_mfma_f32_16x16x32_bf16 v[64:67], v[140:143], v[4:7], v[0:3]
	v_mfma_f32_16x16x32_bf16 v[32:35], v[140:143], v[12:15], v[8:11]
	s_setprio 0

; DI float ex2(float x) { return __builtin_amdgcn_exp2f(x); }
; #define SB0 __builtin_amdgcn_sched_barrier(0)
; template <bool MASKED, class MF>
; DI void flash_update(f32x4 (&s)[4], float scl, float& mx, float& ls, f32x4 (&o)[8], MF maskfn, bool lane_on) {
;   float tmax = -1e30f;
; #pragma unroll
;   for (int kt = 0; kt < 4; ++kt)
; #pragma unroll
;     for (int i = 0; i < 4; ++i) {
;       if (MASKED) { if (maskfn(kt, i)) s[kt][i] = -1e30f; }
;       tmax = fmaxf(tmax, s[kt][i]);
;     }
;   tmax = rowmax4(tmax);
;   if (!lane_on) tmax = -1e30f;
;   const float th = 8.f / scl;
;   if (__any(tmax > mx + th)) {
;     const float mnew = fmaxf(mx, tmax);
;     const float alpha = ex2((mx - mnew) * scl);
;     ls *= alpha;
; #pragma unroll
;     for (int dt = 0; dt < 8; ++dt) o[dt] *= alpha;
;     mx = mnew;
;   }
; DI void ldk2m(bf16x8 (&k)[2], const char* Kb, int m, int kt, int lr, int quad) {
; #pragma unroll
;   for (int kk = 0; kk < 2; ++kk) k[kk] = *(const bf16x8*)(Kb + (kt * 16 + lr) * 256 + (((m * 8 + kk * 4 + quad) ^ lr) << 4));
; }
; DI void diff_S2(f32x4 (&s0)[4], f32x4 (&s1)[4], const char* Kb, const char* Vb, int m, const bf16x8 (&q0)[2], const bf16x8 (&q1)[2],
;                 bf16x8 (&v0)[4], bf16x8 (&v1)[4], int lr, int quad) {
;   bf16x8 f0[2], f1[2], f2[2], f3[2];
;   ldk2m(f0, Kb, m, 0, lr, quad); ldk2m(f1, Kb, m, 1, lr, quad); SB0;
;   ldk2m(f2, Kb, m, 2, lr, quad); s0[0] = mma2(f0, q0); s1[0] = mma2(f0, q1); SB0;
;   ldk2m(f3, Kb, m, 3, lr, quad); s0[1] = mma2(f1, q0); s1[1] = mma2(f1, q1); SB0;
;   ldv4(v0, Vb, 0, lr, quad); s0[2] = mma2(f2, q0); s1[2] = mma2(f2, q1); SB0;
;   ldv4(v1, Vb, 1, lr, quad); s0[3] = mma2(f3, q0); s1[3] = mma2(f3, q1); SB0;
; }
.LBB0_571:
	s_cmp_eq_u32 s7, s63
	s_cbranch_scc1 .LBB0_582
	s_or_b32 s4, s7, s65
	s_lshl_b32 s6, s4, 6
	v_cmp_le_u32_e32 vcc, s6, v211
	s_and_saveexec_b64 s[48:49], vcc
	s_cbranch_execz .LBB0_570
	s_lshl_b32 s4, s7, 15
	s_add_i32 s67, s66, s4
	v_add_u32_e32 v0, s67, v212
	v_add_u32_e32 v28, v0, v214
	v_add_u32_e32 v29, v0, v215
	ds_read_b128 v[0:3], v28
	ds_read_b128 v[4:7], v28 offset:4096
	ds_read_b128 v[8:11], v29
	ds_read_b128 v[12:15], v29 offset:4096
	s_or_b32 s4, s6, 63
	v_cmp_le_u32_e32 vcc, s4, v207
	ds_read_b128 v[16:19], v28 offset:8192
	ds_read_b128 v[20:23], v29 offset:8192
	s_setprio 1
	s_waitcnt lgkmcnt(5)
	v_mfma_f32_16x16x32_bf16 v[24:27], v[0:3], v[96:99], 0
	s_waitcnt lgkmcnt(3)
	v_mfma_f32_16x16x32_bf16 v[172:175], v[8:11], v[100:103], v[24:27]
	s_setprio 0
	s_setprio 1
	v_mfma_f32_16x16x32_bf16 v[0:3], v[0:3], v[104:107], 0
	v_mfma_f32_16x16x32_bf16 v[156:159], v[8:11], v[108:111], v[0:3]
	s_setprio 0
	s_nop 5
	ds_read_b128 v[0:3], v28 offset:12288
	ds_read_b128 v[8:11], v29 offset:12288
	s_setprio 1
	v_mfma_f32_16x16x32_bf16 v[24:27], v[4:7], v[96:99], 0
	s_waitcnt lgkmcnt(4)
	v_mfma_f32_16x16x32_bf16 v[164:167], v[12:15], v[100:103], v[24:27]
	s_setprio 0
	s_setprio 1
	v_mfma_f32_16x16x32_bf16 v[4:7], v[4:7], v[104:107], 0
	v_mfma_f32_16x16x32_bf16 v[148:151], v[12:15], v[108:111], v[4:7]
	s_setprio 0
	v_add3_u32 v12, s67, v217, v216
	ds_read_b128 v[140:143], v12 offset:16384
	ds_read_b128 v[136:139], v12 offset:18432
	ds_read_b128 v[128:131], v12 offset:20480
	ds_read_b128 v[120:123], v12 offset:22528
	s_setprio 1
	s_waitcnt lgkmcnt(7)
	v_mfma_f32_16x16x32_bf16 v[4:7], v[16:19], v[96:99], 0
	s_waitcnt lgkmcnt(6)
	v_mfma_f32_16x16x32_bf16 v[168:171], v[20:23], v[100:103], v[4:7]
	s_setprio 0
	s_setprio 1
	v_mfma_f32_16x16x32_bf16 v[4:7], v[16:19], v[104:107], 0
	v_mfma_f32_16x16x32_bf16 v[152:155], v[20:23], v[108:111], v[4:7]
	s_setprio 0
	ds_read_b128 v[132:135], v12 offset:24576
	ds_read_b128 v[124:127], v12 offset:26624
	ds_read_b128 v[116:119], v12 offset:28672
	ds_read_b128 v[112:115], v12 offset:30720
	s_setprio 1
	s_waitcnt lgkmcnt(0)
	s_waitcnt lgkmcnt(9)
	v_mfma_f32_16x16x32_bf16 v[4:7], v[0:3], v[96:99], 0
	s_waitcnt lgkmcnt(8)
	v_mfma_f32_16x16x32_bf16 v[160:163], v[8:11], v[100:103], v[4:7]
	s_setprio 0
	s_setprio 1
	v_mfma_f32_16x16x32_bf16 v[0:3], v[0:3], v[104:107], 0
	v_mfma_f32_16x16x32_bf16 v[144:147], v[8:11], v[108:111], v[0:3]
	s_setprio 0
	v_add_f32_e32 v232, 0x40b17218, v220
	s_and_saveexec_b64 s[4:5], vcc
	s_xor_b64 s[4:5], exec, s[4:5]
	s_cbranch_execz .LBB0_579
	s_nop 1
	v_max3_f32 v0, v172, s53, v173
	v_max3_f32 v0, v0, v174, v175
	v_max3_f32 v0, v0, v164, v165
	v_max3_f32 v0, v0, v166, v167
	v_max3_f32 v0, v0, v168, v169
	v_max3_f32 v0, v0, v170, v171
	v_max3_f32 v0, v0, v160, v161
	v_max3_f32 v0, v0, v162, v163
	v_mov_b32_e32 v1, v0
	s_nop 1
	v_permlane16_swap_b32_e32 v0, v1
	v_max_f32_e32 v1, v1, v1
	v_max_f32_e32 v0, v0, v0
	v_max_f32_e32 v0, v0, v1
	v_mov_b32_e32 v1, v0
	s_nop 1
	v_permlane32_swap_b32_e32 v0, v1
	v_max_f32_e32 v1, v1, v1
	v_max_f32_e32 v0, v0, v0
	v_max_f32_e32 v0, v0, v1
	v_cmp_gt_f32_e32 vcc, v0, v232
	s_cbranch_vccz .LBB0_576
	v_max_f32_e32 v0, v0, v0
	v_max_f32_e32 v1, v220, v220
	v_max_f32_e32 v1, v1, v0
	v_sub_f32_e32 v0, v220, v1
	v_mul_f32_e32 v0, 0x3fb8aa3b, v0
	v_exp_f32_e32 v0, v0
	v_mov_b32_e32 v220, v1
	v_mul_f32_e32 v213, v213, v0
	v_pk_mul_f32 v[94:95], v[94:95], v[0:1] op_sel_hi:[1,0]
	v_pk_mul_f32 v[92:93], v[92:93], v[0:1] op_sel_hi:[1,0]
	v_pk_mul_f32 v[90:91], v[90:91], v[0:1] op_sel_hi:[1,0]
	v_pk_mul_f32 v[88:89], v[88:89], v[0:1] op_sel_hi:[1,0]
	v_pk_mul_f32 v[86:87], v[86:87], v[0:1] op_sel_hi:[1,0]
	v_pk_mul_f32 v[84:85], v[84:85], v[0:1] op_sel_hi:[1,0]
	v_pk_mul_f32 v[82:83], v[82:83], v[0:1] op_sel_hi:[1,0]
	v_pk_mul_f32 v[80:81], v[80:81], v[0:1] op_sel_hi:[1,0]
	v_pk_mul_f32 v[78:79], v[78:79], v[0:1] op_sel_hi:[1,0]
	v_pk_mul_f32 v[76:77], v[76:77], v[0:1] op_sel_hi:[1,0]
	v_pk_mul_f32 v[74:75], v[74:75], v[0:1] op_sel_hi:[1,0]
	v_pk_mul_f32 v[72:73], v[72:73], v[0:1] op_sel_hi:[1,0]
	v_pk_mul_f32 v[70:71], v[70:71], v[0:1] op_sel_hi:[1,0]
	v_pk_mul_f32 v[68:69], v[68:69], v[0:1] op_sel_hi:[1,0]
	v_pk_mul_f32 v[66:67], v[66:67], v[0:1] op_sel_hi:[1,0]
	v_pk_mul_f32 v[64:65], v[64:65], v[0:1] op_sel_hi:[1,0]

; DI f32x4 mfma16(bf16x8 a, bf16x8 b, f32x4 c) { return __builtin_amdgcn_mfma_f32_16x16x32_bf16(a, b, c, 0, 0, 0); }
; #define SB0 __builtin_amdgcn_sched_barrier(0)
; DI void ldk4(bf16x8 (&k)[4], const char* Kb, int kt, int lr, int quad) {
; #pragma unroll
;   for (int kk = 0; kk < 4; ++kk) k[kk] = *(const bf16x8*)(Kb + (kt * 16 + lr) * 256 + (((kk * 4 + quad) ^ lr) << 4));
; }
; DI f32x4 mma4(const bf16x8 (&k)[4], const bf16x8 (&qf)[4]) {
;   f32x4 a = zero4();
;   __builtin_amdgcn_s_setprio(1);
; #pragma unroll
;   for (int kk = 0; kk < 4; ++kk) a = mfma16(k[kk], qf[kk], a);
;   __builtin_amdgcn_s_setprio(0);
;   return a;
; }
; DI void ldv4(bf16x8 (&v)[4], const char* Vb, int qtr, int lr, int quad) {
; #pragma unroll
;   for (int i = 0; i < 4; ++i) v[i] = load_vfrag(Vb, qtr >> 1, 4 * (qtr & 1) + i, lr, quad);
; }
; DI void nsa_S(f32x4 (&s)[4], const char* Kb, const char* Vb, const bf16x8 (&qf)[4], bf16x8 (&v0)[4], int lr, int quad) {
;   bf16x8 k0[4], k1[4], k2[4], k3[4];
;   ldk4(k0, Kb, 0, lr, quad); SB0;
;   ldk4(k1, Kb, 1, lr, quad); s[0] = mma4(k0, qf); SB0;
;   ldk4(k2, Kb, 2, lr, quad); s[1] = mma4(k1, qf); SB0;
;   ldk4(k3, Kb, 3, lr, quad); s[2] = mma4(k2, qf); SB0;
;   ldv4(v0, Vb, 0, lr, quad); s[3] = mma4(k3, qf); SB0;
; }
.LBB0_752:
	v_lshl_add_u32 v14, s13, 15, v9
	v_add_u32_e32 v15, v14, v235
	v_add_u32_e32 v67, v14, v237
	v_add_u32_e32 v66, v14, v236
	ds_read_b128 v[10:13], v15
	ds_read_b128 v[34:37], v66
	v_add_u32_e32 v14, v14, v238
	ds_read_b128 v[38:41], v67
	ds_read_b128 v[42:45], v14
	s_xor_b64 s[10:11], s[10:11], -1
	ds_read_b128 v[46:49], v15 offset:4096
	ds_read_b128 v[50:53], v66 offset:4096
	ds_read_b128 v[54:57], v67 offset:4096
	ds_read_b128 v[58:61], v14 offset:4096
	s_setprio 1
	s_waitcnt lgkmcnt(7)
	v_mfma_f32_16x16x32_bf16 v[10:13], v[10:13], v[18:21], 0
	s_waitcnt lgkmcnt(6)
	v_mfma_f32_16x16x32_bf16 v[10:13], v[34:37], v[22:25], v[10:13]
	s_waitcnt lgkmcnt(5)
	v_mfma_f32_16x16x32_bf16 v[10:13], v[38:41], v[26:29], v[10:13]
	s_waitcnt lgkmcnt(4)
	v_mfma_f32_16x16x32_bf16 v[10:13], v[42:45], v[30:33], v[10:13]
	s_setprio 0
	ds_read_b128 v[34:37], v15 offset:8192
	ds_read_b128 v[38:41], v66 offset:8192
	ds_read_b128 v[42:45], v67 offset:8192
	ds_read_b128 v[62:65], v14 offset:8192
	s_setprio 1
	s_waitcnt lgkmcnt(7)
	v_mfma_f32_16x16x32_bf16 v[46:49], v[46:49], v[18:21], 0
	s_waitcnt lgkmcnt(6)
	v_mfma_f32_16x16x32_bf16 v[46:49], v[50:53], v[22:25], v[46:49]
	s_waitcnt lgkmcnt(5)
	v_mfma_f32_16x16x32_bf16 v[46:49], v[54:57], v[26:29], v[46:49]
	s_waitcnt lgkmcnt(4)
	v_mfma_f32_16x16x32_bf16 v[46:49], v[58:61], v[30:33], v[46:49]
	s_setprio 0
	ds_read_b128 v[50:53], v15 offset:12288
	ds_read_b128 v[54:57], v66 offset:12288
	ds_read_b128 v[58:61], v67 offset:12288
	ds_read_b128 v[66:69], v14 offset:12288
	s_setprio 1
	s_waitcnt lgkmcnt(7)
	v_mfma_f32_16x16x32_bf16 v[34:37], v[34:37], v[18:21], 0
	s_waitcnt lgkmcnt(6)
	v_mfma_f32_16x16x32_bf16 v[34:37], v[38:41], v[22:25], v[34:37]
	s_waitcnt lgkmcnt(5)
	v_mfma_f32_16x16x32_bf16 v[34:37], v[42:45], v[26:29], v[34:37]
	s_waitcnt lgkmcnt(4)
	v_mfma_f32_16x16x32_bf16 v[34:37], v[62:65], v[30:33], v[34:37]
	s_setprio 0
	s_setprio 1
	s_waitcnt lgkmcnt(3)
	v_mfma_f32_16x16x32_bf16 v[38:41], v[50:53], v[18:21], 0
	s_waitcnt lgkmcnt(2)
	v_mfma_f32_16x16x32_bf16 v[38:41], v[54:57], v[22:25], v[38:41]
	s_waitcnt lgkmcnt(1)
	v_mfma_f32_16x16x32_bf16 v[38:41], v[58:61], v[26:29], v[38:41]
	s_waitcnt lgkmcnt(0)
; DI float ex2(float x) { return __builtin_amdgcn_exp2f(x); }
; DI void nsa_item(const Params& p, int b, int g, int qb, char* smem, int tid) {
;     ...
;     float tmax = -1e30f;
; #pragma unroll
;     for (int kt = 0; kt < 4; ++kt)
; #pragma unroll
;       for (int i = 0; i < 4; ++i) {
;         int cc = j * 64 + kt * 16 + quad * 4 + i;
;         float v = (cc <= cmax) ? s[kt][i] * SCL : -1e30f;
;         s[kt][i] = v; tmax = fmaxf(tmax, v);
;       }
;     tmax = rowmax4(tmax);
;     float mnew = fmaxf(mx, tmax), rs = 0.f;
; #pragma unroll
;     for (int kt = 0; kt < 4; ++kt)
; #pragma unroll
;       for (int i = 0; i < 4; ++i) { float v = s[kt][i]; rs += (v > -1e29f) ? ex2(v - mnew) : 0.f; }
;     ls = ls * ex2(mx - mnew) + rs; mx = mnew;
	v_mfma_f32_16x16x32_bf16 v[38:41], v[66:69], v[30:33], v[38:41]
	s_setprio 0
	v_lshl_or_b32 v14, s12, 6, v214
	v_mul_f32_e32 v10, 0x3e0293ee, v10
	v_cmp_le_i32_e32 vcc, v14, v78
	v_mul_f32_e32 v11, 0x3e0293ee, v11
	v_or_b32_e32 v15, 2, v14
	v_cndmask_b32_e32 v10, v231, v10, vcc
	v_cmp_lt_i32_e32 vcc, v14, v78
	v_mul_f32_e32 v12, 0x3e0293ee, v12
	v_mul_f32_e32 v13, 0x3e0293ee, v13
	v_cndmask_b32_e32 v11, v231, v11, vcc
	v_cmp_le_i32_e32 vcc, v15, v78
	v_or_b32_e32 v15, 3, v14
	v_mul_f32_e32 v42, 0x3e0293ee, v46
	v_cndmask_b32_e32 v12, v231, v12, vcc
	v_cmp_le_i32_e32 vcc, v15, v78
	v_or_b32_e32 v15, 16, v14
	v_mul_f32_e32 v43, 0x3e0293ee, v47
	v_cndmask_b32_e32 v13, v231, v13, vcc
	v_cmp_le_i32_e32 vcc, v15, v78
	v_mul_f32_e32 v44, 0x3e0293ee, v48
	v_mul_f32_e32 v45, 0x3e0293ee, v49
	v_cndmask_b32_e32 v15, v231, v42, vcc
	v_or_b32_e32 v42, 17, v14
	v_cmp_le_i32_e32 vcc, v42, v78
	v_mul_f32_e32 v34, 0x3e0293ee, v34
	v_mul_f32_e32 v35, 0x3e0293ee, v35
	v_cndmask_b32_e32 v42, v231, v43, vcc
	v_or_b32_e32 v43, 18, v14
	v_cmp_le_i32_e32 vcc, v43, v78
	v_mul_f32_e32 v36, 0x3e0293ee, v36
	v_mul_f32_e32 v37, 0x3e0293ee, v37
	v_cndmask_b32_e32 v43, v231, v44, vcc
	v_or_b32_e32 v44, 19, v14
	v_cmp_le_i32_e32 vcc, v44, v78
	v_mul_f32_e32 v38, 0x3e0293ee, v38
	v_mul_f32_e32 v39, 0x3e0293ee, v39
	v_cndmask_b32_e32 v44, v231, v45, vcc
	v_or_b32_e32 v45, 32, v14
	v_cmp_le_i32_e32 vcc, v45, v78
	v_or_b32_e32 v45, 33, v14
	v_mul_f32_e32 v40, 0x3e0293ee, v40
	v_cndmask_b32_e32 v34, v231, v34, vcc
	v_cmp_le_i32_e32 vcc, v45, v78
	v_or_b32_e32 v45, 34, v14
	v_mul_f32_e32 v41, 0x3e0293ee, v41
	v_cndmask_b32_e32 v35, v231, v35, vcc
	v_cmp_le_i32_e32 vcc, v45, v78
	v_or_b32_e32 v45, 35, v14
	s_nop 0
	v_cndmask_b32_e32 v36, v231, v36, vcc
	v_cmp_le_i32_e32 vcc, v45, v78
	v_or_b32_e32 v45, 48, v14
	s_nop 0
	v_cndmask_b32_e32 v37, v231, v37, vcc
	v_cmp_le_i32_e32 vcc, v45, v78
	v_or_b32_e32 v45, 49, v14
	s_nop 0
	v_cndmask_b32_e32 v38, v231, v38, vcc
	v_cmp_le_i32_e32 vcc, v45, v78
	v_or_b32_e32 v45, 50, v14
	v_or_b32_e32 v14, 51, v14
	v_cndmask_b32_e32 v39, v231, v39, vcc
	v_cmp_le_i32_e32 vcc, v45, v78
	s_nop 1
	v_cndmask_b32_e32 v40, v231, v40, vcc
	v_cmp_le_i32_e32 vcc, v14, v78
	s_nop 1
	v_cndmask_b32_e32 v14, v231, v41, vcc
	v_max3_f32 v41, v10, s41, v11
	v_max3_f32 v41, v41, v12, v13
	v_max3_f32 v41, v41, v15, v42
	v_max3_f32 v41, v41, v43, v44
	v_max3_f32 v41, v41, v34, v35
	v_max3_f32 v41, v41, v36, v37
	v_max3_f32 v41, v41, v38, v39
	v_max3_f32 v41, v41, v40, v14
	v_mov_b32_e32 v45, v41
	s_nop 1
	v_permlane16_swap_b32_e32 v41, v45
	v_max_f32_e32 v45, v45, v45
	v_max_f32_e32 v41, v41, v41
	v_max_f32_e32 v41, v41, v45
	v_mov_b32_e32 v45, v41
	s_nop 1
	v_permlane32_swap_b32_e32 v41, v45
	v_max3_f32 v41, v94, v41, v45
	v_sub_f32_e32 v45, v10, v41
	v_exp_f32_e32 v45, v45
	v_cmp_lt_f32_e32 vcc, s33, v10
	v_sub_f32_e32 v46, v12, v41
	v_exp_f32_e32 v46, v46
	v_add_f32_e32 v45, 0, v45
	v_cndmask_b32_e32 v10, 0, v45, vcc
	v_sub_f32_e32 v45, v11, v41
	v_exp_f32_e32 v45, v45
	v_cmp_lt_f32_e32 vcc, s33, v11
	s_nop 1
	v_cndmask_b32_e32 v11, 0, v45, vcc
	v_cmp_lt_f32_e32 vcc, s33, v12
	v_add_f32_e32 v10, v11, v10
	v_sub_f32_e32 v12, v15, v41
	v_cndmask_b32_e32 v11, 0, v46, vcc
	v_add_f32_e32 v10, v11, v10
	v_sub_f32_e32 v11, v13, v41
	v_exp_f32_e32 v11, v11
	v_exp_f32_e32 v12, v12
	v_cmp_lt_f32_e32 vcc, s33, v13
	s_nop 1
	v_cndmask_b32_e32 v11, 0, v11, vcc
	v_cmp_lt_f32_e32 vcc, s33, v15
	v_add_f32_e32 v10, v11, v10
	s_nop 0
	v_cndmask_b32_e32 v11, 0, v12, vcc
	v_add_f32_e32 v10, v11, v10
	v_sub_f32_e32 v11, v42, v41
	v_exp_f32_e32 v11, v11
	v_sub_f32_e32 v12, v43, v41
	v_exp_f32_e32 v12, v12
	v_cmp_lt_f32_e32 vcc, s33, v42
	s_nop 1
	v_cndmask_b32_e32 v11, 0, v11, vcc
	v_cmp_lt_f32_e32 vcc, s33, v43
	v_add_f32_e32 v10, v11, v10
	s_nop 0
	v_cndmask_b32_e32 v11, 0, v12, vcc
	v_add_f32_e32 v10, v11, v10
	v_sub_f32_e32 v11, v44, v41
	v_exp_f32_e32 v11, v11
	v_sub_f32_e32 v12, v34, v41
	v_exp_f32_e32 v12, v12
	v_cmp_lt_f32_e32 vcc, s33, v44
	s_nop 1
	v_cndmask_b32_e32 v11, 0, v11, vcc
	v_cmp_lt_f32_e32 vcc, s33, v34
	v_add_f32_e32 v10, v11, v10
	s_nop 0
	v_cndmask_b32_e32 v11, 0, v12, vcc
	v_add_f32_e32 v10, v11, v10
	v_sub_f32_e32 v11, v35, v41
	v_exp_f32_e32 v11, v11
	v_sub_f32_e32 v12, v36, v41
	v_exp_f32_e32 v12, v12
	v_cmp_lt_f32_e32 vcc, s33, v35
	s_nop 1
	v_cndmask_b32_e32 v11, 0, v11, vcc
	v_cmp_lt_f32_e32 vcc, s33, v36
	v_add_f32_e32 v10, v11, v10
	s_nop 0
	v_cndmask_b32_e32 v11, 0, v12, vcc
	v_add_f32_e32 v10, v11, v10
	v_sub_f32_e32 v11, v37, v41
	v_exp_f32_e32 v11, v11
	v_sub_f32_e32 v12, v38, v41
	v_exp_f32_e32 v12, v12
	v_cmp_lt_f32_e32 vcc, s33, v37
	s_nop 1
	v_cndmask_b32_e32 v11, 0, v11, vcc
	v_cmp_lt_f32_e32 vcc, s33, v38
	v_add_f32_e32 v10, v11, v10
	s_nop 0
	v_cndmask_b32_e32 v11, 0, v12, vcc
	v_add_f32_e32 v10, v11, v10
	v_sub_f32_e32 v11, v39, v41
	v_exp_f32_e32 v11, v11
	v_sub_f32_e32 v12, v40, v41
	v_exp_f32_e32 v12, v12
	v_cmp_lt_f32_e32 vcc, s33, v39
	s_nop 1
	v_cndmask_b32_e32 v11, 0, v11, vcc
	v_cmp_lt_f32_e32 vcc, s33, v40
	v_add_f32_e32 v10, v11, v10
	s_nop 0
	v_cndmask_b32_e32 v11, 0, v12, vcc
	v_add_f32_e32 v10, v11, v10
	v_sub_f32_e32 v11, v14, v41
	v_exp_f32_e32 v11, v11
	v_sub_f32_e32 v12, v94, v41
	v_exp_f32_e32 v12, v12
	v_cmp_lt_f32_e32 vcc, s33, v14
	v_mov_b32_e32 v94, v41
	s_nop 0
	v_cndmask_b32_e32 v11, 0, v11, vcc
	v_add_f32_e32 v10, v11, v10
	v_fmac_f32_e32 v10, v7, v12
	v_mov_b32_e32 v7, v10
	s_mov_b32 s13, 1
	s_andn2_b64 vcc, exec, s[10:11]
	s_mov_b64 s[10:11], 0
	s_cbranch_vccz .LBB0_755

; DI float ex2(float x) { return __builtin_amdgcn_exp2f(x); }
; #define SB0 __builtin_amdgcn_sched_barrier(0)
; DI void nsa_S(f32x4 (&s)[4], const char* Kb, const char* Vb, const bf16x8 (&qf)[4], bf16x8 (&v0)[4], int lr, int quad) {
;   bf16x8 k0[4], k1[4], k2[4], k3[4];
;   ldk4(k0, Kb, 0, lr, quad); SB0;
;   ldk4(k1, Kb, 1, lr, quad); s[0] = mma4(k0, qf); SB0;
;   ldk4(k2, Kb, 2, lr, quad); s[1] = mma4(k1, qf); SB0;
;   ldk4(k3, Kb, 3, lr, quad); s[2] = mma4(k2, qf); SB0;
;   ldv4(v0, Vb, 0, lr, quad); s[3] = mma4(k3, qf); SB0;
; }
; DI void nsa_item(const Params& p, int b, int g, int qb, char* smem, int tid) {
;     ...
;     float* irow = imp + qi * 132;
; #pragma unroll
;     for (int kt = 0; kt < 4; ++kt) {
;       float a = 0.f;
; #pragma unroll
;       for (int i = 0; i < 4; ++i) {
;         int cc = j * 64 + kt * 16 + quad * 4 + i;
;         float pv = (cc <= cmax) ? ex2(s[kt][i] * SCL - mx) * inv : 0.f;
;         s[kt][i] = pv; a += pv;
;       }
;       if (a != 0.f) {
;         int n1 = j * 16 + kt * 4 + quad;
;         atomicAdd(irow + n1, a);
;         if (s[kt][3] != 0.f) atomicAdd(irow + n1 + 1, s[kt][3]);
;       }
;     }
.LBB0_768:
	s_or_b32 s10, s17, s15
	s_cmp_ge_u32 s10, s14
	s_cbranch_scc1 .LBB0_767
	s_lshl_b32 s11, s17, 15
	s_add_i32 s17, s16, s11
	v_add_u32_e32 v8, s17, v234
	v_add_u32_e32 v104, v8, v235
	v_add_u32_e32 v108, v8, v237
	v_add_u32_e32 v105, v8, v236
	ds_read_b128 v[0:3], v104
	ds_read_b128 v[4:7], v105
	v_add_u32_e32 v112, v8, v238
	ds_read_b128 v[8:11], v108
	ds_read_b128 v[12:15], v112
	ds_read_b128 v[66:69], v104 offset:4096
	ds_read_b128 v[70:73], v105 offset:4096
	ds_read_b128 v[74:77], v108 offset:4096
	ds_read_b128 v[96:99], v112 offset:4096
	s_setprio 1
	s_waitcnt lgkmcnt(7)
	v_mfma_f32_16x16x32_bf16 v[0:3], v[0:3], v[18:21], 0
	s_waitcnt lgkmcnt(6)
	v_mfma_f32_16x16x32_bf16 v[0:3], v[4:7], v[22:25], v[0:3]
	s_waitcnt lgkmcnt(5)
	v_mfma_f32_16x16x32_bf16 v[0:3], v[8:11], v[26:29], v[0:3]
	s_waitcnt lgkmcnt(4)
	v_mfma_f32_16x16x32_bf16 v[100:103], v[12:15], v[30:33], v[0:3]
	s_setprio 0
	s_nop 5
	ds_read_b128 v[0:3], v104 offset:8192
	ds_read_b128 v[4:7], v105 offset:8192
	ds_read_b128 v[8:11], v108 offset:8192
	ds_read_b128 v[12:15], v112 offset:8192
	s_setprio 1
	s_waitcnt lgkmcnt(7)
	v_mfma_f32_16x16x32_bf16 v[66:69], v[66:69], v[18:21], 0
	s_waitcnt lgkmcnt(6)
	v_mfma_f32_16x16x32_bf16 v[66:69], v[70:73], v[22:25], v[66:69]
	s_waitcnt lgkmcnt(5)
	v_mfma_f32_16x16x32_bf16 v[66:69], v[74:77], v[26:29], v[66:69]
	s_waitcnt lgkmcnt(4)
	v_mfma_f32_16x16x32_bf16 v[74:77], v[96:99], v[30:33], v[66:69]
	s_setprio 0
	s_nop 5
	ds_read_b128 v[66:69], v104 offset:12288
	ds_read_b128 v[104:107], v105 offset:12288
	ds_read_b128 v[108:111], v108 offset:12288
	ds_read_b128 v[112:115], v112 offset:12288
	s_setprio 1
	s_waitcnt lgkmcnt(7)
	v_mfma_f32_16x16x32_bf16 v[0:3], v[0:3], v[18:21], 0
	s_waitcnt lgkmcnt(6)
	v_mfma_f32_16x16x32_bf16 v[0:3], v[4:7], v[22:25], v[0:3]
	s_waitcnt lgkmcnt(5)
	v_mfma_f32_16x16x32_bf16 v[0:3], v[8:11], v[26:29], v[0:3]
	s_waitcnt lgkmcnt(4)
	v_mfma_f32_16x16x32_bf16 v[70:73], v[12:15], v[30:33], v[0:3]
	s_setprio 0
	s_nop 5
	v_add_u32_e32 v0, s17, v242
	v_add_u32_e32 v96, v0, v241
	ds_read_b128 v[0:3], v96 offset:16384
	ds_read_b128 v[4:7], v96 offset:18432
	ds_read_b128 v[8:11], v96 offset:20480
	ds_read_b128 v[12:15], v96 offset:22528
	s_setprio 1
	s_waitcnt lgkmcnt(7)
	v_mfma_f32_16x16x32_bf16 v[66:69], v[66:69], v[18:21], 0
	s_waitcnt lgkmcnt(6)
	v_mfma_f32_16x16x32_bf16 v[66:69], v[104:107], v[22:25], v[66:69]
	s_waitcnt lgkmcnt(5)
	v_mfma_f32_16x16x32_bf16 v[66:69], v[108:111], v[26:29], v[66:69]
	s_waitcnt lgkmcnt(4)
	v_mfma_f32_16x16x32_bf16 v[66:69], v[112:115], v[30:33], v[66:69]
	s_setprio 0
	v_fma_f32 v97, v100, s40, -v94
	v_exp_f32_e32 v97, v97
	v_fma_f32 v98, v101, s40, -v94
	v_exp_f32_e32 v98, v98
	s_lshl_b32 s18, s10, 6
	v_fma_f32 v100, v102, s40, -v94
	v_fma_f32 v101, v103, s40, -v94
	v_or_b32_e32 v99, s18, v214
	v_exp_f32_e32 v100, v100
	v_exp_f32_e32 v101, v101
	v_mul_f32_e32 v97, v86, v97
	v_cmp_le_i32_e32 vcc, v99, v78
	v_mul_f32_e32 v98, v86, v98
	v_or_b32_e32 v103, 3, v99
	v_cndmask_b32_e32 v97, 0, v97, vcc
	v_cmp_lt_i32_e32 vcc, v99, v78
	v_add_f32_e32 v104, 0, v97
	v_pk_mul_f32 v[100:101], v[86:87], v[100:101]
	v_cndmask_b32_e32 v98, 0, v98, vcc
	v_add_f32_e32 v102, v98, v104
	v_or_b32_e32 v104, 2, v99
	v_cmp_le_i32_e32 vcc, v103, v79
	s_lshl_b32 s10, s10, 4
	s_nop 0
	v_cndmask_b32_e32 v99, 0, v101, vcc
	v_cmp_le_i32_e32 vcc, v104, v78
	s_nop 1
	v_cndmask_b32_e32 v100, 0, v100, vcc
	v_add_f32_e32 v101, v100, v102
	v_add_f32_e32 v102, v99, v101
	v_cmp_neq_f32_e32 vcc, 0, v102
	v_lshl_add_u32 v101, s10, 2, v95
	s_and_saveexec_b64 s[10:11], vcc
	s_cbranch_execz .LBB0_772
	s_waitcnt vmcnt(0)
	ds_add_f32 v101, v102
	v_cmp_neq_f32_e32 vcc, 0, v99
	s_and_b64 exec, exec, vcc
	ds_add_f32 v101, v99 offset:4

; DI f32x4 mfma16(bf16x8 a, bf16x8 b, f32x4 c) { return __builtin_amdgcn_mfma_f32_16x16x32_bf16(a, b, c, 0, 0, 0); }
; #define SB0 __builtin_amdgcn_sched_barrier(0)
; DI void nsa_PV(f32x4 (&o)[8], const char* Vb, const bf16x8 (&pf)[2], bf16x8 (&v0)[4], int lr, int quad) {
;   bf16x8 v1[4], v2[4], v3[4];
;   SB0;
;   ldv4(v1, Vb, 1, lr, quad);
;   __builtin_amdgcn_s_setprio(1);
; #pragma unroll
;   for (int i = 0; i < 4; ++i) o[i] = mfma16(v0[i], pf[0], o[i]);
;   __builtin_amdgcn_s_setprio(0);
;   SB0;
;   ldv4(v2, Vb, 2, lr, quad);
;   __builtin_amdgcn_s_setprio(1);
; #pragma unroll
;   for (int i = 0; i < 4; ++i) o[4 + i] = mfma16(v1[i], pf[0], o[4 + i]);
;   __builtin_amdgcn_s_setprio(0);
;   SB0;
;   ldv4(v3, Vb, 3, lr, quad);
;   __builtin_amdgcn_s_setprio(1);
; #pragma unroll
;   for (int i = 0; i < 4; ++i) o[i] = mfma16(v2[i], pf[1], o[i]);
;   __builtin_amdgcn_s_setprio(0);
;   SB0;
;   __builtin_amdgcn_s_setprio(1);
; #pragma unroll
;   for (int i = 0; i < 4; ++i) o[4 + i] = mfma16(v3[i], pf[1], o[4 + i]);
;   __builtin_amdgcn_s_setprio(0);
; }
.LBB0_781:
	s_or_b64 exec, exec, s[10:11]
	s_xor_b64 s[10:11], s[8:9], -1
	v_cvt_pk_bf16_f32 v98, v97, v98
	v_cvt_pk_bf16_f32 v99, v100, v99
	v_cvt_pk_bf16_f32 v100, v74, v75
	v_cvt_pk_bf16_f32 v101, v77, v76
	v_cvt_pk_bf16_f32 v70, v70, v71
	v_cvt_pk_bf16_f32 v71, v73, v72
	v_cvt_pk_bf16_f32 v72, v66, v67
	v_cvt_pk_bf16_f32 v73, v69, v68
	ds_read_b128 v[66:69], v96 offset:24576
	ds_read_b128 v[74:77], v96 offset:26624
	ds_read_b128 v[102:105], v96 offset:28672
	ds_read_b128 v[106:109], v96 offset:30720
	s_setprio 1
	s_waitcnt lgkmcnt(4)
	v_mfma_f32_16x16x32_bf16 v[0:3], v[0:3], v[98:101], v[62:65]
	v_mfma_f32_16x16x32_bf16 v[4:7], v[4:7], v[98:101], v[58:61]
	v_mfma_f32_16x16x32_bf16 v[8:11], v[8:11], v[98:101], v[54:57]
	v_mfma_f32_16x16x32_bf16 v[12:15], v[12:15], v[98:101], v[50:53]
	s_setprio 0
	v_add3_u32 v58, s17, v243, v241
	s_nop 0
	ds_read_b128 v[50:53], v58 offset:16384
	ds_read_b128 v[54:57], v58 offset:18432
	ds_read_b128 v[110:113], v58 offset:20480
	ds_read_b128 v[114:117], v58 offset:22528
	s_setprio 1
	s_waitcnt lgkmcnt(7)
	v_mfma_f32_16x16x32_bf16 v[46:49], v[66:69], v[98:101], v[46:49]
	s_waitcnt lgkmcnt(6)
	v_mfma_f32_16x16x32_bf16 v[42:45], v[74:77], v[98:101], v[42:45]
	s_waitcnt lgkmcnt(5)
	v_mfma_f32_16x16x32_bf16 v[38:41], v[102:105], v[98:101], v[38:41]
	s_waitcnt lgkmcnt(4)
	v_mfma_f32_16x16x32_bf16 v[34:37], v[106:109], v[98:101], v[34:37]
	s_setprio 0
	ds_read_b128 v[66:69], v58 offset:24576
	ds_read_b128 v[74:77], v58 offset:26624
	ds_read_b128 v[96:99], v58 offset:28672
	ds_read_b128 v[100:103], v58 offset:30720
	s_setprio 1
	s_waitcnt lgkmcnt(7)
	v_mfma_f32_16x16x32_bf16 v[62:65], v[50:53], v[70:73], v[0:3]
	s_waitcnt lgkmcnt(6)
	v_mfma_f32_16x16x32_bf16 v[58:61], v[54:57], v[70:73], v[4:7]
	s_waitcnt lgkmcnt(5)
	v_mfma_f32_16x16x32_bf16 v[54:57], v[110:113], v[70:73], v[8:11]
	s_waitcnt lgkmcnt(4)
	v_mfma_f32_16x16x32_bf16 v[50:53], v[114:117], v[70:73], v[12:15]
	s_setprio 0
	s_setprio 1
	s_waitcnt lgkmcnt(3)
	v_mfma_f32_16x16x32_bf16 v[46:49], v[66:69], v[70:73], v[46:49]
	s_waitcnt lgkmcnt(2)
	v_mfma_f32_16x16x32_bf16 v[42:45], v[74:77], v[70:73], v[42:45]
	s_waitcnt lgkmcnt(1)
	v_mfma_f32_16x16x32_bf16 v[38:41], v[96:99], v[70:73], v[38:41]
	s_waitcnt lgkmcnt(0)
	v_mfma_f32_16x16x32_bf16 v[34:37], v[100:103], v[70:73], v[34:37]
	s_setprio 0
	s_mov_b32 s17, 1
	s_mov_b64 s[8:9], 0
	s_and_b64 vcc, exec, s[10:11]
	s_cbranch_vccz .LBB0_768

; #define SB0 __builtin_amdgcn_sched_barrier(0)
; DI void nsa_S(f32x4 (&s)[4], const char* Kb, const char* Vb, const bf16x8 (&qf)[4], bf16x8 (&v0)[4], int lr, int quad) {
;   bf16x8 k0[4], k1[4], k2[4], k3[4];
;   ldk4(k0, Kb, 0, lr, quad); SB0;
;   ldk4(k1, Kb, 1, lr, quad); s[0] = mma4(k0, qf); SB0;
;   ldk4(k2, Kb, 2, lr, quad); s[1] = mma4(k1, qf); SB0;
;   ldk4(k3, Kb, 3, lr, quad); s[2] = mma4(k2, qf); SB0;
;   ldv4(v0, Vb, 0, lr, quad); s[3] = mma4(k3, qf); SB0;
; }
; DI void nsa_item(const Params& p, int b, int g, int qb, char* smem, int tid) {
;     ...
;       const bool sb = (sel[qi * 4 + (j >> 5)] >> (j & 31)) & 1u;
;       if (!__any(sb)) return;
;       f32x4 s[4];
;       bf16x8 va[4];
;       nsa_S(s, Kb, Vb, qf, va, lr, quad);
;       auto mf = [&](int kt, int i) __attribute__((always_inline)) { return j * 64 + kt * 16 + quad * 4 + i > qp; };
;       if (j == cur) flash_update<true>(s, SCL, mx2, l2, o, mf, sb);
;       else flash_update<false>(s, SCL, mx2, l2, o, mf, sb);
.LBB0_817:
	s_or_b32 s59, s48, s56
	s_cmp_gt_u32 s59, s2
	s_cbranch_scc1 .LBB0_816
	ds_read_b32 v0, v172
	s_and_b32 s38, s59, 31
	s_waitcnt lgkmcnt(0)
	v_lshrrev_b32_e32 v1, s59, v0
	v_bfe_u32 v0, v0, s38, 1
	v_and_b32_e32 v1, 1, v1
	v_cmp_ne_u32_e32 vcc, 0, v0
	v_cmp_eq_u32_e64 s[38:39], 1, v1
	s_cbranch_vccz .LBB0_829
	s_lshl_b32 s48, s48, 15
	s_add_i32 s58, s57, s48
	v_add_u32_e32 v8, s58, v234
	v_add_u32_e32 v122, v8, v235
	v_add_u32_e32 v124, v8, v237
	v_add_u32_e32 v123, v8, v236
	ds_read_b128 v[0:3], v122
	ds_read_b128 v[4:7], v123
	v_add_u32_e32 v125, v8, v238
	ds_read_b128 v[8:11], v124
	ds_read_b128 v[12:15], v125
	ds_read_b128 v[98:101], v122 offset:4096
	ds_read_b128 v[102:105], v123 offset:4096
	ds_read_b128 v[106:109], v124 offset:4096
	ds_read_b128 v[110:113], v125 offset:4096
	s_setprio 1
	s_waitcnt lgkmcnt(7)
	v_mfma_f32_16x16x32_bf16 v[0:3], v[0:3], v[18:21], 0
	s_waitcnt lgkmcnt(6)
	v_mfma_f32_16x16x32_bf16 v[0:3], v[4:7], v[22:25], v[0:3]
	s_waitcnt lgkmcnt(5)
	v_mfma_f32_16x16x32_bf16 v[0:3], v[8:11], v[26:29], v[0:3]
	s_waitcnt lgkmcnt(4)
	v_mfma_f32_16x16x32_bf16 v[114:117], v[12:15], v[30:33], v[0:3]
	s_setprio 0
	s_nop 5
	ds_read_b128 v[0:3], v122 offset:8192
	ds_read_b128 v[4:7], v123 offset:8192
	ds_read_b128 v[8:11], v124 offset:8192
	ds_read_b128 v[12:15], v125 offset:8192
	s_setprio 1
	s_waitcnt lgkmcnt(7)
	v_mfma_f32_16x16x32_bf16 v[98:101], v[98:101], v[18:21], 0
	s_waitcnt lgkmcnt(6)
	v_mfma_f32_16x16x32_bf16 v[98:101], v[102:105], v[22:25], v[98:101]
	s_waitcnt lgkmcnt(5)
	v_mfma_f32_16x16x32_bf16 v[98:101], v[106:109], v[26:29], v[98:101]
	s_waitcnt lgkmcnt(4)
	v_mfma_f32_16x16x32_bf16 v[118:121], v[110:113], v[30:33], v[98:101]
	s_setprio 0
	ds_read_b128 v[126:129], v122 offset:12288
	ds_read_b128 v[130:133], v123 offset:12288
	ds_read_b128 v[134:137], v124 offset:12288
	ds_read_b128 v[138:141], v125 offset:12288
	s_setprio 1
	s_waitcnt lgkmcnt(7)
	v_mfma_f32_16x16x32_bf16 v[0:3], v[0:3], v[18:21], 0
	s_waitcnt lgkmcnt(6)
	v_mfma_f32_16x16x32_bf16 v[0:3], v[4:7], v[22:25], v[0:3]
	s_waitcnt lgkmcnt(5)
	v_mfma_f32_16x16x32_bf16 v[0:3], v[8:11], v[26:29], v[0:3]
	s_waitcnt lgkmcnt(4)
	v_mfma_f32_16x16x32_bf16 v[122:125], v[12:15], v[30:33], v[0:3]
	s_setprio 0
	s_nop 5
	v_add_u32_e32 v0, s58, v242
	v_add_u32_e32 v174, v0, v241
	ds_read_b128 v[98:101], v174 offset:16384
	ds_read_b128 v[102:105], v174 offset:18432
	ds_read_b128 v[106:109], v174 offset:20480
	ds_read_b128 v[110:113], v174 offset:22528
	s_setprio 1
	s_waitcnt lgkmcnt(7)
	v_mfma_f32_16x16x32_bf16 v[0:3], v[126:129], v[18:21], 0
	s_waitcnt lgkmcnt(6)
	v_mfma_f32_16x16x32_bf16 v[0:3], v[130:133], v[22:25], v[0:3]
	s_waitcnt lgkmcnt(5)
	v_mfma_f32_16x16x32_bf16 v[0:3], v[134:137], v[26:29], v[0:3]
	s_waitcnt lgkmcnt(4)
	v_mfma_f32_16x16x32_bf16 v[126:129], v[138:141], v[30:33], v[0:3]
	s_setprio 0
	s_mov_b64 s[48:49], -1
	s_cmp_lg_u32 s59, s2
	v_add_f32_e32 v176, 0x427af232, v173
	s_cbranch_scc0 .LBB0_823
	s_nop 1
	v_max3_f32 v0, v114, s41, v115
	v_max3_f32 v0, v0, v116, v117
	v_max3_f32 v0, v0, v118, v119
	v_max3_f32 v0, v0, v120, v121
	v_max3_f32 v0, v0, v122, v123
	v_max3_f32 v0, v0, v124, v125
	v_max3_f32 v0, v0, v126, v127
	v_max3_f32 v0, v0, v128, v129
	v_mov_b32_e32 v1, v0
	s_nop 1
	v_permlane16_swap_b32_e32 v0, v1
	v_max_f32_e32 v1, v1, v1
	v_max_f32_e32 v0, v0, v0
	v_max_f32_e32 v0, v0, v1
	v_mov_b32_e32 v1, v0
	s_nop 1
	v_permlane32_swap_b32_e32 v0, v1
	v_max_f32_e32 v1, v1, v1
	v_max_f32_e32 v0, v0, v0
	v_max_f32_e32 v0, v0, v1
	v_cndmask_b32_e64 v0, v231, v0, s[38:39]
	v_mov_b64_e32 v[160:161], v[68:69]
	v_mov_b64_e32 v[156:157], v[72:73]
	v_mov_b64_e32 v[152:153], v[76:77]
	v_mov_b64_e32 v[148:149], v[80:81]
	v_mov_b64_e32 v[144:145], v[84:85]
	v_mov_b64_e32 v[140:141], v[88:89]
	v_mov_b64_e32 v[136:137], v[92:93]
	v_mov_b64_e32 v[132:133], v[96:97]
	v_cmp_gt_f32_e32 vcc, v0, v176
	v_mov_b64_e32 v[158:159], v[66:67]
	v_mov_b64_e32 v[154:155], v[70:71]
	v_mov_b64_e32 v[150:151], v[74:75]
	v_mov_b64_e32 v[146:147], v[78:79]
	v_mov_b64_e32 v[142:143], v[82:83]
	v_mov_b64_e32 v[138:139], v[86:87]
	v_mov_b64_e32 v[134:135], v[90:91]
	v_mov_b64_e32 v[130:131], v[94:95]
	v_mov_b32_e32 v177, v170
	v_mov_b32_e32 v175, v173
	s_cbranch_vccz .LBB0_822
	v_max_f32_e32 v0, v0, v0
	v_max_f32_e32 v1, v173, v173
	v_max_f32_e32 v175, v1, v0
	v_sub_f32_e32 v0, v173, v175
	v_mul_f32_e32 v0, 0x3e0293ee, v0
	v_exp_f32_e32 v0, v0
	s_nop 0
	v_mul_f32_e32 v177, v170, v0
	v_pk_mul_f32 v[132:133], v[96:97], v[0:1] op_sel_hi:[1,0]
	v_pk_mul_f32 v[130:131], v[94:95], v[0:1] op_sel_hi:[1,0]
	v_pk_mul_f32 v[136:137], v[92:93], v[0:1] op_sel_hi:[1,0]
	v_pk_mul_f32 v[134:135], v[90:91], v[0:1] op_sel_hi:[1,0]
	v_pk_mul_f32 v[140:141], v[88:89], v[0:1] op_sel_hi:[1,0]
	v_pk_mul_f32 v[138:139], v[86:87], v[0:1] op_sel_hi:[1,0]
	v_pk_mul_f32 v[144:145], v[84:85], v[0:1] op_sel_hi:[1,0]
	v_pk_mul_f32 v[142:143], v[82:83], v[0:1] op_sel_hi:[1,0]
	v_pk_mul_f32 v[148:149], v[80:81], v[0:1] op_sel_hi:[1,0]
	v_pk_mul_f32 v[146:147], v[78:79], v[0:1] op_sel_hi:[1,0]
	v_pk_mul_f32 v[152:153], v[76:77], v[0:1] op_sel_hi:[1,0]
	v_pk_mul_f32 v[150:151], v[74:75], v[0:1] op_sel_hi:[1,0]
	v_pk_mul_f32 v[156:157], v[72:73], v[0:1] op_sel_hi:[1,0]
	v_pk_mul_f32 v[154:155], v[70:71], v[0:1] op_sel_hi:[1,0]
	v_pk_mul_f32 v[160:161], v[68:69], v[0:1] op_sel_hi:[1,0]
	v_pk_mul_f32 v[158:159], v[66:67], v[0:1] op_sel_hi:[1,0]

; DI f32x4 mfma16(bf16x8 a, bf16x8 b, f32x4 c) { return __builtin_amdgcn_mfma_f32_16x16x32_bf16(a, b, c, 0, 0, 0); }
; #define SB0 __builtin_amdgcn_sched_barrier(0)
; DI void nsa_PV(f32x4 (&o)[8], const char* Vb, const bf16x8 (&pf)[2], bf16x8 (&v0)[4], int lr, int quad) {
;   bf16x8 v1[4], v2[4], v3[4];
;   SB0;
;   ldv4(v1, Vb, 1, lr, quad);
;   __builtin_amdgcn_s_setprio(1);
; #pragma unroll
;   for (int i = 0; i < 4; ++i) o[i] = mfma16(v0[i], pf[0], o[i]);
;   __builtin_amdgcn_s_setprio(0);
;   SB0;
;   ldv4(v2, Vb, 2, lr, quad);
;   __builtin_amdgcn_s_setprio(1);
; #pragma unroll
;   for (int i = 0; i < 4; ++i) o[4 + i] = mfma16(v1[i], pf[0], o[4 + i]);
;   __builtin_amdgcn_s_setprio(0);
;   SB0;
;   ldv4(v3, Vb, 3, lr, quad);
;   __builtin_amdgcn_s_setprio(1);
; #pragma unroll
;   for (int i = 0; i < 4; ++i) o[i] = mfma16(v2[i], pf[1], o[i]);
;   __builtin_amdgcn_s_setprio(0);
;   SB0;
;   __builtin_amdgcn_s_setprio(1);
; #pragma unroll
;   for (int i = 0; i < 4; ++i) o[4 + i] = mfma16(v3[i], pf[1], o[4 + i]);
;   __builtin_amdgcn_s_setprio(0);
; }
.LBB0_828:
	v_add_f32_e32 v170, v177, v178
	v_cvt_pk_bf16_f32 v0, v0, v1
	v_cvt_pk_bf16_f32 v1, v2, v3
	v_cvt_pk_bf16_f32 v2, v4, v5
	v_cvt_pk_bf16_f32 v3, v6, v7
	v_cvt_pk_bf16_f32 v4, v8, v9
	v_cvt_pk_bf16_f32 v5, v10, v11
	v_cvt_pk_bf16_f32 v6, v12, v13
	v_cvt_pk_bf16_f32 v7, v14, v15
	ds_read_b128 v[8:11], v174 offset:24576
	ds_read_b128 v[12:15], v174 offset:26624
	ds_read_b128 v[66:69], v174 offset:28672
	ds_read_b128 v[70:73], v174 offset:30720
	s_setprio 1
	s_waitcnt lgkmcnt(4)
	v_mfma_f32_16x16x32_bf16 v[74:77], v[98:101], v[0:3], v[130:133]
	v_mfma_f32_16x16x32_bf16 v[78:81], v[102:105], v[0:3], v[134:137]
	v_mfma_f32_16x16x32_bf16 v[82:85], v[106:109], v[0:3], v[138:141]
	v_mfma_f32_16x16x32_bf16 v[98:101], v[110:113], v[0:3], v[142:145]
	s_setprio 0
	v_add3_u32 v94, s58, v243, v241
	ds_read_b128 v[86:89], v94 offset:16384
	ds_read_b128 v[90:93], v94 offset:18432
	ds_read_b128 v[102:105], v94 offset:20480
	ds_read_b128 v[106:109], v94 offset:22528
	s_setprio 1
	s_waitcnt lgkmcnt(5)
	v_mfma_f32_16x16x32_bf16 v[66:69], v[66:69], v[0:3], v[154:157]
	v_mfma_f32_16x16x32_bf16 v[8:11], v[8:11], v[0:3], v[146:149]
	v_mfma_f32_16x16x32_bf16 v[12:15], v[12:15], v[0:3], v[150:153]
	s_waitcnt lgkmcnt(4)
	v_mfma_f32_16x16x32_bf16 v[0:3], v[70:73], v[0:3], v[158:161]
	s_setprio 0
	ds_read_b128 v[70:73], v94 offset:24576
	ds_read_b128 v[110:113], v94 offset:26624
	ds_read_b128 v[114:117], v94 offset:28672
	ds_read_b128 v[118:121], v94 offset:30720
	s_setprio 1
	s_waitcnt lgkmcnt(7)
	v_mfma_f32_16x16x32_bf16 v[94:97], v[86:89], v[4:7], v[74:77]
	s_waitcnt lgkmcnt(6)
	v_mfma_f32_16x16x32_bf16 v[90:93], v[90:93], v[4:7], v[78:81]
	s_waitcnt lgkmcnt(5)
	v_mfma_f32_16x16x32_bf16 v[86:89], v[102:105], v[4:7], v[82:85]
	s_waitcnt lgkmcnt(4)
	v_mfma_f32_16x16x32_bf16 v[82:85], v[106:109], v[4:7], v[98:101]
	s_setprio 0
	s_setprio 1
	s_waitcnt lgkmcnt(3)
	v_mfma_f32_16x16x32_bf16 v[78:81], v[70:73], v[4:7], v[8:11]
	s_waitcnt lgkmcnt(2)
	v_mfma_f32_16x16x32_bf16 v[74:77], v[110:113], v[4:7], v[12:15]
	s_waitcnt lgkmcnt(1)
	v_mfma_f32_16x16x32_bf16 v[70:73], v[114:117], v[4:7], v[66:69]
	s_waitcnt lgkmcnt(0)
	v_mfma_f32_16x16x32_bf16 v[66:69], v[118:121], v[4:7], v[0:3]
	s_setprio 0
	v_mov_b32_e32 v173, v175

; #define SB0 __builtin_amdgcn_sched_barrier(0)
; DI void nsa_S(f32x4 (&s)[4], const char* Kb, const char* Vb, const bf16x8 (&qf)[4], bf16x8 (&v0)[4], int lr, int quad) {
;   bf16x8 k0[4], k1[4], k2[4], k3[4];
;   ldk4(k0, Kb, 0, lr, quad); SB0;
;   ldk4(k1, Kb, 1, lr, quad); s[0] = mma4(k0, qf); SB0;
;   ldk4(k2, Kb, 2, lr, quad); s[1] = mma4(k1, qf); SB0;
;   ldk4(k3, Kb, 3, lr, quad); s[2] = mma4(k2, qf); SB0;
;   ldv4(v0, Vb, 0, lr, quad); s[3] = mma4(k3, qf); SB0;
; }
; DI void nsa_item(const Params& p, int b, int g, int qb, char* smem, int tid) {
;     ...
;       nsa_S(s, Kb, Vb, qf, va, lr, quad);
;       auto mf = [&](int kt, int i) __attribute__((always_inline)) {
;         int key = j * 64 + kt * 16 + quad * 4 + i;
;         return (key > qp) || (key <= qp - 512);
;       };
;       if (j * 64 + 63 <= q0 && j * 64 > q0 + 31 - 512) flash_update<false>(s, SCL, mx2, l2, o, mf, true);
;       else flash_update<true>(s, SCL, mx2, l2, o, mf, true);
.LBB0_844:
	s_lshl_b32 s5, s6, 15
	s_add_i32 s24, s23, s5
	v_add_u32_e32 v8, s24, v234
	v_add_u32_e32 v146, v8, v235
	v_add_u32_e32 v151, v8, v237
	v_add_u32_e32 v150, v8, v236
	ds_read_b128 v[0:3], v146
	ds_read_b128 v[4:7], v150
	v_add_u32_e32 v152, v8, v238
	ds_read_b128 v[8:11], v151
	ds_read_b128 v[12:15], v152
	ds_read_b128 v[130:133], v146 offset:4096
	ds_read_b128 v[134:137], v150 offset:4096
	ds_read_b128 v[138:141], v151 offset:4096
	ds_read_b128 v[142:145], v152 offset:4096
	s_setprio 1
	s_waitcnt lgkmcnt(7)
	v_mfma_f32_16x16x32_bf16 v[0:3], v[0:3], v[18:21], 0
	s_waitcnt lgkmcnt(6)
	v_mfma_f32_16x16x32_bf16 v[0:3], v[4:7], v[22:25], v[0:3]
	s_waitcnt lgkmcnt(5)
	v_mfma_f32_16x16x32_bf16 v[0:3], v[8:11], v[26:29], v[0:3]
	s_waitcnt lgkmcnt(4)
	v_mfma_f32_16x16x32_bf16 v[158:161], v[12:15], v[30:33], v[0:3]
	s_setprio 0
	s_nop 5
	ds_read_b128 v[0:3], v146 offset:8192
	ds_read_b128 v[4:7], v150 offset:8192
	ds_read_b128 v[8:11], v151 offset:8192
	ds_read_b128 v[12:15], v152 offset:8192
	s_setprio 1
	s_waitcnt lgkmcnt(7)
	v_mfma_f32_16x16x32_bf16 v[130:133], v[130:133], v[18:21], 0
	s_waitcnt lgkmcnt(6)
	v_mfma_f32_16x16x32_bf16 v[130:133], v[134:137], v[22:25], v[130:133]
	s_waitcnt lgkmcnt(5)
	v_mfma_f32_16x16x32_bf16 v[130:133], v[138:141], v[26:29], v[130:133]
	s_waitcnt lgkmcnt(4)
	v_mfma_f32_16x16x32_bf16 v[154:157], v[142:145], v[30:33], v[130:133]
	s_setprio 0
	ds_read_b128 v[146:149], v146 offset:12288
	ds_read_b128 v[162:165], v150 offset:12288
	ds_read_b128 v[166:169], v151 offset:12288
	ds_read_b128 v[170:173], v152 offset:12288
	s_setprio 1
	s_waitcnt lgkmcnt(7)
	v_mfma_f32_16x16x32_bf16 v[0:3], v[0:3], v[18:21], 0
	s_waitcnt lgkmcnt(6)
	v_mfma_f32_16x16x32_bf16 v[0:3], v[4:7], v[22:25], v[0:3]
	s_waitcnt lgkmcnt(5)
	v_mfma_f32_16x16x32_bf16 v[0:3], v[8:11], v[26:29], v[0:3]
	s_waitcnt lgkmcnt(4)
	v_mfma_f32_16x16x32_bf16 v[150:153], v[12:15], v[30:33], v[0:3]
	s_setprio 0
	s_nop 5
	v_add_u32_e32 v0, s24, v242
	v_add_u32_e32 v247, v0, v241
	ds_read_b128 v[130:133], v247 offset:16384
	ds_read_b128 v[134:137], v247 offset:18432
	ds_read_b128 v[138:141], v247 offset:20480
	ds_read_b128 v[142:145], v247 offset:22528
	s_setprio 1
	s_waitcnt lgkmcnt(7)
	v_mfma_f32_16x16x32_bf16 v[0:3], v[146:149], v[18:21], 0
	s_waitcnt lgkmcnt(6)
	v_mfma_f32_16x16x32_bf16 v[0:3], v[162:165], v[22:25], v[0:3]
	s_waitcnt lgkmcnt(5)
	v_mfma_f32_16x16x32_bf16 v[0:3], v[166:169], v[26:29], v[0:3]
	s_waitcnt lgkmcnt(4)
	v_mfma_f32_16x16x32_bf16 v[146:149], v[170:173], v[30:33], v[0:3]
	s_setprio 0
	s_lshl_b32 s6, s4, 6
	s_or_b32 s4, s6, 63
	s_cmp_le_u32 s4, s85
	s_cselect_b64 s[4:5], -1, 0
	s_cmp_gt_i32 s6, s21
	s_cselect_b64 s[8:9], -1, 0
	s_and_b64 s[8:9], s[4:5], s[8:9]
	s_mov_b64 s[4:5], -1
	s_andn2_b64 vcc, exec, s[8:9]
	v_add_f32_e32 v249, 0x427af232, v246
	s_cbranch_vccz .LBB0_849
; DI float ex2(float x) { return __builtin_amdgcn_exp2f(x); }
; template <bool MASKED, class MF>
; DI void flash_update(f32x4 (&s)[4], float scl, float& mx, float& ls, f32x4 (&o)[8], MF maskfn, bool lane_on) {
;   float tmax = -1e30f;
; #pragma unroll
;   for (int kt = 0; kt < 4; ++kt)
; #pragma unroll
;     for (int i = 0; i < 4; ++i) {
;       if (MASKED) { if (maskfn(kt, i)) s[kt][i] = -1e30f; }
;       tmax = fmaxf(tmax, s[kt][i]);
;     }
;   tmax = rowmax4(tmax);
;   if (!lane_on) tmax = -1e30f;
;   const float th = 8.f / scl;
;   if (__any(tmax > mx + th)) {
;     const float mnew = fmaxf(mx, tmax);
;     const float alpha = ex2((mx - mnew) * scl);
;     ls *= alpha;
; #pragma unroll
;     for (int dt = 0; dt < 8; ++dt) o[dt] *= alpha;
;     mx = mnew;
;   }
; DI void nsa_item(const Params& p, int b, int g, int qb, char* smem, int tid) {
;     ...
;       auto mf = [&](int kt, int i) __attribute__((always_inline)) {
;         int key = j * 64 + kt * 16 + quad * 4 + i;
;         return (key > qp) || (key <= qp - 512);
;       };
;       if (j * 64 + 63 <= q0 && j * 64 > q0 + 31 - 512) flash_update<false>(s, SCL, mx2, l2, o, mf, true);
;       else flash_update<true>(s, SCL, mx2, l2, o, mf, true);
	v_or_b32_e32 v15, s6, v214
	v_cmp_gt_i32_e32 vcc, v15, v233
	v_cmp_le_i32_e64 s[4:5], v15, v245
	s_or_b64 vcc, vcc, s[4:5]
	v_cndmask_b32_e32 v0, v158, v231, vcc
	v_cmp_ge_i32_e32 vcc, v15, v233
	v_cmp_lt_i32_e64 s[4:5], v15, v245
	s_or_b64 vcc, vcc, s[4:5]
	v_or_b32_e32 v2, 2, v15
	v_cndmask_b32_e32 v1, v159, v231, vcc
	v_cmp_gt_i32_e32 vcc, v2, v233
	v_cmp_le_i32_e64 s[4:5], v2, v245
	s_or_b64 vcc, vcc, s[4:5]
	v_or_b32_e32 v3, 3, v15
	v_cndmask_b32_e32 v2, v160, v231, vcc
	v_cmp_gt_i32_e32 vcc, v3, v233
	v_cmp_le_i32_e64 s[4:5], v3, v245
	s_or_b64 s[4:5], vcc, s[4:5]
	v_max3_f32 v4, v0, s41, v1
	v_cndmask_b32_e64 v3, v161, v231, s[4:5]
	v_max3_f32 v6, v4, v2, v3
	v_or_b32_e32 v4, 16, v15
	v_cmp_gt_i32_e32 vcc, v4, v233
	v_cmp_le_i32_e64 s[6:7], v4, v245
	s_or_b64 vcc, vcc, s[6:7]
	v_or_b32_e32 v5, 17, v15
	v_cndmask_b32_e32 v4, v154, v231, vcc
	v_cmp_gt_i32_e32 vcc, v5, v233
	v_cmp_le_i32_e64 s[6:7], v5, v245
	s_or_b64 vcc, vcc, s[6:7]
	v_cndmask_b32_e32 v5, v155, v231, vcc
	v_max3_f32 v8, v6, v4, v5
	v_or_b32_e32 v6, 18, v15
	v_cmp_gt_i32_e32 vcc, v6, v233
	v_cmp_le_i32_e64 s[6:7], v6, v245
	s_or_b64 vcc, vcc, s[6:7]
	v_or_b32_e32 v7, 19, v15
	v_cndmask_b32_e32 v6, v156, v231, vcc
	v_cmp_gt_i32_e32 vcc, v7, v233
	v_cmp_le_i32_e64 s[6:7], v7, v245
	s_or_b64 s[6:7], vcc, s[6:7]
	v_or_b32_e32 v9, 33, v15
	v_cndmask_b32_e64 v7, v157, v231, s[6:7]
	v_max3_f32 v10, v8, v6, v7
	v_or_b32_e32 v8, 32, v15
	v_cmp_gt_i32_e32 vcc, v8, v233
	v_cmp_le_i32_e64 s[8:9], v8, v245
	s_or_b64 vcc, vcc, s[8:9]
	v_cndmask_b32_e32 v8, v150, v231, vcc
	v_cmp_gt_i32_e32 vcc, v9, v233
	v_cmp_le_i32_e64 s[8:9], v9, v245
	s_or_b64 vcc, vcc, s[8:9]
	v_cndmask_b32_e32 v9, v151, v231, vcc
	v_max3_f32 v12, v10, v8, v9
	v_or_b32_e32 v10, 34, v15
	v_cmp_gt_i32_e32 vcc, v10, v233
	v_cmp_le_i32_e64 s[8:9], v10, v245
	s_or_b64 vcc, vcc, s[8:9]
	v_or_b32_e32 v11, 35, v15
	v_cndmask_b32_e32 v10, v152, v231, vcc
	v_cmp_gt_i32_e32 vcc, v11, v233
	v_cmp_le_i32_e64 s[8:9], v11, v245
	s_or_b64 s[8:9], vcc, s[8:9]
	v_or_b32_e32 v13, 49, v15
	v_cndmask_b32_e64 v11, v153, v231, s[8:9]
	v_max3_f32 v14, v12, v10, v11
	v_or_b32_e32 v12, 48, v15
	v_cmp_gt_i32_e32 vcc, v12, v233
	v_cmp_le_i32_e64 s[10:11], v12, v245
	s_or_b64 vcc, vcc, s[10:11]
	v_cndmask_b32_e32 v12, v146, v231, vcc
	v_cmp_gt_i32_e32 vcc, v13, v233
	v_cmp_le_i32_e64 s[10:11], v13, v245
	s_or_b64 vcc, vcc, s[10:11]
	v_cndmask_b32_e32 v13, v147, v231, vcc
	v_max3_f32 v162, v14, v12, v13
	v_or_b32_e32 v14, 50, v15
	v_cmp_gt_i32_e32 vcc, v14, v233
	v_cmp_le_i32_e64 s[10:11], v14, v245
	s_or_b64 vcc, vcc, s[10:11]
	v_or_b32_e32 v15, 51, v15
	v_cndmask_b32_e32 v14, v148, v231, vcc
	v_cmp_gt_i32_e32 vcc, v15, v233
	v_cmp_le_i32_e64 s[10:11], v15, v245
	s_or_b64 s[10:11], vcc, s[10:11]
	s_nop 0
	v_cndmask_b32_e64 v15, v149, v231, s[10:11]
	v_max3_f32 v162, v162, v14, v15
	v_mov_b32_e32 v163, v162
	s_nop 1
	v_permlane16_swap_b32_e32 v162, v163
	v_max_f32_e32 v163, v163, v163
	v_max_f32_e32 v162, v162, v162
	v_max_f32_e32 v162, v162, v163
	v_mov_b32_e32 v163, v162
	s_nop 1
	v_permlane32_swap_b32_e32 v162, v163
	v_max_f32_e32 v163, v163, v163
	v_max_f32_e32 v162, v162, v162
	v_max_f32_e32 v162, v162, v163
	v_cmp_gt_f32_e32 vcc, v162, v249
	s_cbranch_vccz .LBB0_847
	v_max_f32_e32 v7, v162, v162
	v_max_f32_e32 v11, v246, v246
	v_max_f32_e32 v248, v11, v7
	v_sub_f32_e32 v7, v246, v248
	v_mul_f32_e32 v7, 0x3e0293ee, v7
	v_exp_f32_e32 v190, v7
	v_cndmask_b32_e64 v3, v161, v231, s[4:5]
	v_cndmask_b32_e64 v7, v157, v231, s[6:7]
	v_cndmask_b32_e64 v11, v153, v231, s[8:9]
	v_cndmask_b32_e64 v15, v149, v231, s[10:11]
	v_mul_f32_e32 v250, v244, v190
	v_pk_mul_f32 v[164:165], v[128:129], v[190:191] op_sel_hi:[1,0]
	v_pk_mul_f32 v[162:163], v[126:127], v[190:191] op_sel_hi:[1,0]
	v_pk_mul_f32 v[168:169], v[124:125], v[190:191] op_sel_hi:[1,0]
	v_pk_mul_f32 v[166:167], v[122:123], v[190:191] op_sel_hi:[1,0]
	v_pk_mul_f32 v[172:173], v[120:121], v[190:191] op_sel_hi:[1,0]
	v_pk_mul_f32 v[170:171], v[118:119], v[190:191] op_sel_hi:[1,0]
	v_pk_mul_f32 v[176:177], v[116:117], v[190:191] op_sel_hi:[1,0]
	v_pk_mul_f32 v[174:175], v[114:115], v[190:191] op_sel_hi:[1,0]
	v_pk_mul_f32 v[180:181], v[112:113], v[190:191] op_sel_hi:[1,0]
	v_pk_mul_f32 v[178:179], v[110:111], v[190:191] op_sel_hi:[1,0]
	v_pk_mul_f32 v[184:185], v[108:109], v[190:191] op_sel_hi:[1,0]
	v_pk_mul_f32 v[182:183], v[106:107], v[190:191] op_sel_hi:[1,0]
	v_pk_mul_f32 v[188:189], v[104:105], v[190:191] op_sel_hi:[1,0]
	v_pk_mul_f32 v[186:187], v[102:103], v[190:191] op_sel_hi:[1,0]
	v_pk_mul_f32 v[192:193], v[100:101], v[190:191] op_sel_hi:[1,0]
	v_pk_mul_f32 v[190:191], v[98:99], v[190:191] op_sel_hi:[1,0]
	s_branch .LBB0_848

; DI f32x4 mfma16(bf16x8 a, bf16x8 b, f32x4 c) { return __builtin_amdgcn_mfma_f32_16x16x32_bf16(a, b, c, 0, 0, 0); }
; #define SB0 __builtin_amdgcn_sched_barrier(0)
; DI void nsa_PV(f32x4 (&o)[8], const char* Vb, const bf16x8 (&pf)[2], bf16x8 (&v0)[4], int lr, int quad) {
;   bf16x8 v1[4], v2[4], v3[4];
;   SB0;
;   ldv4(v1, Vb, 1, lr, quad);
;   __builtin_amdgcn_s_setprio(1);
; #pragma unroll
;   for (int i = 0; i < 4; ++i) o[i] = mfma16(v0[i], pf[0], o[i]);
;   __builtin_amdgcn_s_setprio(0);
;   SB0;
;   ldv4(v2, Vb, 2, lr, quad);
;   __builtin_amdgcn_s_setprio(1);
; #pragma unroll
;   for (int i = 0; i < 4; ++i) o[4 + i] = mfma16(v1[i], pf[0], o[4 + i]);
;   __builtin_amdgcn_s_setprio(0);
;   SB0;
;   ldv4(v3, Vb, 3, lr, quad);
;   __builtin_amdgcn_s_setprio(1);
; #pragma unroll
;   for (int i = 0; i < 4; ++i) o[i] = mfma16(v2[i], pf[1], o[i]);
;   __builtin_amdgcn_s_setprio(0);
;   SB0;
;   __builtin_amdgcn_s_setprio(1);
; #pragma unroll
;   for (int i = 0; i < 4; ++i) o[4 + i] = mfma16(v3[i], pf[1], o[4 + i]);
;   __builtin_amdgcn_s_setprio(0);
; }
.LBB0_853:
	s_xor_b64 s[4:5], s[14:15], -1
	v_add_f32_e32 v244, v250, v251
	v_cvt_pk_bf16_f32 v0, v0, v1
	v_cvt_pk_bf16_f32 v1, v2, v3
	v_cvt_pk_bf16_f32 v2, v4, v5
	v_cvt_pk_bf16_f32 v3, v6, v7
	v_cvt_pk_bf16_f32 v4, v8, v9
	v_cvt_pk_bf16_f32 v5, v10, v11
	v_cvt_pk_bf16_f32 v6, v12, v13
	v_cvt_pk_bf16_f32 v7, v14, v15
	ds_read_b128 v[8:11], v247 offset:24576
	ds_read_b128 v[12:15], v247 offset:26624
	ds_read_b128 v[98:101], v247 offset:28672
	ds_read_b128 v[102:105], v247 offset:30720
	s_setprio 1
	s_waitcnt lgkmcnt(4)
	v_mfma_f32_16x16x32_bf16 v[106:109], v[130:133], v[0:3], v[162:165]
	v_mfma_f32_16x16x32_bf16 v[110:113], v[134:137], v[0:3], v[166:169]
	v_mfma_f32_16x16x32_bf16 v[114:117], v[138:141], v[0:3], v[170:173]
	v_mfma_f32_16x16x32_bf16 v[130:133], v[142:145], v[0:3], v[174:177]
	s_setprio 0
	v_add3_u32 v126, s24, v243, v241
	ds_read_b128 v[118:121], v126 offset:16384
	ds_read_b128 v[122:125], v126 offset:18432
	ds_read_b128 v[134:137], v126 offset:20480
	ds_read_b128 v[138:141], v126 offset:22528
	s_setprio 1
	s_waitcnt lgkmcnt(5)
	v_mfma_f32_16x16x32_bf16 v[98:101], v[98:101], v[0:3], v[186:189]
	v_mfma_f32_16x16x32_bf16 v[8:11], v[8:11], v[0:3], v[178:181]
	v_mfma_f32_16x16x32_bf16 v[12:15], v[12:15], v[0:3], v[182:185]
	s_waitcnt lgkmcnt(4)
	v_mfma_f32_16x16x32_bf16 v[0:3], v[102:105], v[0:3], v[190:193]
	s_setprio 0
	ds_read_b128 v[102:105], v126 offset:24576
	ds_read_b128 v[142:145], v126 offset:26624
	ds_read_b128 v[146:149], v126 offset:28672
	ds_read_b128 v[150:153], v126 offset:30720
	s_setprio 1
	s_waitcnt lgkmcnt(7)
	v_mfma_f32_16x16x32_bf16 v[126:129], v[118:121], v[4:7], v[106:109]
	s_waitcnt lgkmcnt(6)
	v_mfma_f32_16x16x32_bf16 v[122:125], v[122:125], v[4:7], v[110:113]
	s_waitcnt lgkmcnt(5)
	v_mfma_f32_16x16x32_bf16 v[118:121], v[134:137], v[4:7], v[114:117]
	s_waitcnt lgkmcnt(4)
	v_mfma_f32_16x16x32_bf16 v[114:117], v[138:141], v[4:7], v[130:133]
	s_setprio 0
	s_setprio 1
	s_waitcnt lgkmcnt(3)
	v_mfma_f32_16x16x32_bf16 v[110:113], v[102:105], v[4:7], v[8:11]
	s_waitcnt lgkmcnt(2)
	v_mfma_f32_16x16x32_bf16 v[106:109], v[142:145], v[4:7], v[12:15]
	s_waitcnt lgkmcnt(1)
	v_mfma_f32_16x16x32_bf16 v[102:105], v[146:149], v[4:7], v[98:101]
	s_waitcnt lgkmcnt(0)
	v_mfma_f32_16x16x32_bf16 v[98:101], v[150:153], v[4:7], v[0:3]
	s_setprio 0
	s_mov_b32 s6, 1
	s_mov_b64 s[14:15], 0
	s_and_b64 vcc, exec, s[4:5]
	s_cbranch_vccnz .LBB0_855
